# last down-projection (phase 14): write-through (sc0 sc1) output stores so its rows are not dirty in L2 at kernel end
# baseline (speedup 1.0000x reference)
.LBB0_1447:
	v_lshl_add_u32 v152, s55, 8, v1
	v_lshl_or_b32 v144, s54, 8, v147
	v_readlane_b32 s2, v252, 2
	v_ashrrev_i32_e32 v145, 31, v144
	v_readlane_b32 s3, v252, 3
	v_ashrrev_i32_e32 v153, 31, v152
	v_pk_add_f32 v[128:129], v[128:129], 0 op_sel_hi:[1,0]
	v_lshl_add_u64 v[154:155], v[144:145], 1, s[2:3]
	v_lshlrev_b64 v[144:145], 11, v[152:153]
	v_lshl_add_u64 v[144:145], v[154:155], 0, v[144:145]
	v_pk_add_f32 v[126:127], v[126:127], 0 op_sel_hi:[1,0]
	v_pk_add_f32 v[156:157], v[124:125], 0 op_sel_hi:[1,0]
	v_pk_add_f32 v[124:125], v[122:123], 0 op_sel_hi:[1,0]
	v_cvt_pk_bf16_f32 v122, v126, v127
	v_cvt_pk_bf16_f32 v123, v128, v129
	v_pk_add_f32 v[118:119], v[118:119], 0 op_sel_hi:[1,0]
	v_cvt_pk_bf16_f32 v124, v124, v125
	v_cvt_pk_bf16_f32 v125, v156, v157
	global_store_dwordx4 v[144:145], v[122:125], off sc0 sc1
	v_pk_add_f32 v[120:121], v[120:121], 0 op_sel_hi:[1,0]
	v_pk_add_f32 v[114:115], v[114:115], 0 op_sel_hi:[1,0]
	v_pk_add_f32 v[122:123], v[112:113], 0 op_sel_hi:[1,0]
	v_pk_add_f32 v[112:113], v[110:111], 0 op_sel_hi:[1,0]
	v_cvt_pk_bf16_f32 v110, v118, v119
	v_cvt_pk_bf16_f32 v111, v120, v121
	v_pk_add_f32 v[102:103], v[102:103], 0 op_sel_hi:[1,0]
	v_cvt_pk_bf16_f32 v112, v112, v113
	v_cvt_pk_bf16_f32 v113, v122, v123
	global_store_dwordx4 v[144:145], v[110:113], off offset:256 sc0 sc1
	v_pk_add_f32 v[104:105], v[104:105], 0 op_sel_hi:[1,0]
	v_pk_add_f32 v[98:99], v[98:99], 0 op_sel_hi:[1,0]
	v_or_b32_e32 v110, 16, v152
	v_ashrrev_i32_e32 v111, 31, v110
	v_lshlrev_b64 v[110:111], 11, v[110:111]
	v_lshl_add_u64 v[110:111], v[154:155], 0, v[110:111]
	v_pk_add_f32 v[112:113], v[116:117], 0 op_sel_hi:[1,0]
	v_pk_add_f32 v[116:117], v[108:109], 0 op_sel_hi:[1,0]
	v_pk_add_f32 v[108:109], v[106:107], 0 op_sel_hi:[1,0]
	v_cvt_pk_bf16_f32 v106, v114, v115
	v_cvt_pk_bf16_f32 v107, v112, v113
	v_pk_add_f32 v[86:87], v[86:87], 0 op_sel_hi:[1,0]
	v_cvt_pk_bf16_f32 v108, v108, v109
	v_cvt_pk_bf16_f32 v109, v116, v117
	global_store_dwordx4 v[110:111], v[106:109], off sc0 sc1
	v_pk_add_f32 v[88:89], v[88:89], 0 op_sel_hi:[1,0]
	v_pk_add_f32 v[82:83], v[82:83], 0 op_sel_hi:[1,0]
	v_pk_add_f32 v[106:107], v[96:97], 0 op_sel_hi:[1,0]
	v_pk_add_f32 v[96:97], v[94:95], 0 op_sel_hi:[1,0]
	v_cvt_pk_bf16_f32 v94, v102, v103
	v_cvt_pk_bf16_f32 v95, v104, v105
	v_pk_add_f32 v[72:73], v[72:73], 0 op_sel_hi:[1,0]
	v_cvt_pk_bf16_f32 v96, v96, v97
	v_cvt_pk_bf16_f32 v97, v106, v107
	global_store_dwordx4 v[110:111], v[94:97], off offset:256 sc0 sc1
	v_pk_add_f32 v[70:71], v[70:71], 0 op_sel_hi:[1,0]
	v_pk_add_f32 v[62:63], v[62:63], 0 op_sel_hi:[1,0]
	v_or_b32_e32 v94, 32, v152
	v_ashrrev_i32_e32 v95, 31, v94
	v_lshlrev_b64 v[94:95], 11, v[94:95]
	v_lshl_add_u64 v[94:95], v[154:155], 0, v[94:95]
	v_pk_add_f32 v[96:97], v[100:101], 0 op_sel_hi:[1,0]
	v_pk_add_f32 v[100:101], v[92:93], 0 op_sel_hi:[1,0]
	v_pk_add_f32 v[92:93], v[90:91], 0 op_sel_hi:[1,0]
	v_cvt_pk_bf16_f32 v90, v98, v99
	v_cvt_pk_bf16_f32 v91, v96, v97
	v_pk_add_f32 v[64:65], v[64:65], 0 op_sel_hi:[1,0]
	v_cvt_pk_bf16_f32 v92, v92, v93
	v_cvt_pk_bf16_f32 v93, v100, v101
	global_store_dwordx4 v[94:95], v[90:93], off sc0 sc1
	v_pk_add_f32 v[56:57], v[56:57], 0 op_sel_hi:[1,0]
	v_pk_add_f32 v[54:55], v[54:55], 0 op_sel_hi:[1,0]
	v_pk_add_f32 v[90:91], v[80:81], 0 op_sel_hi:[1,0]
	v_pk_add_f32 v[80:81], v[78:79], 0 op_sel_hi:[1,0]
	v_cvt_pk_bf16_f32 v78, v86, v87
	v_cvt_pk_bf16_f32 v79, v88, v89
	v_pk_add_f32 v[50:51], v[50:51], 0 op_sel_hi:[1,0]
	v_cvt_pk_bf16_f32 v80, v80, v81
	v_cvt_pk_bf16_f32 v81, v90, v91
	global_store_dwordx4 v[94:95], v[78:81], off offset:256 sc0 sc1
	v_pk_add_f32 v[40:41], v[40:41], 0 op_sel_hi:[1,0]
	v_pk_add_f32 v[38:39], v[38:39], 0 op_sel_hi:[1,0]
	v_or_b32_e32 v78, 48, v152
	v_ashrrev_i32_e32 v79, 31, v78
	v_lshlrev_b64 v[78:79], 11, v[78:79]
	v_lshl_add_u64 v[78:79], v[154:155], 0, v[78:79]
	v_pk_add_f32 v[80:81], v[84:85], 0 op_sel_hi:[1,0]
	v_pk_add_f32 v[84:85], v[76:77], 0 op_sel_hi:[1,0]
	v_pk_add_f32 v[76:77], v[74:75], 0 op_sel_hi:[1,0]
	v_cvt_pk_bf16_f32 v74, v82, v83
	v_cvt_pk_bf16_f32 v75, v80, v81
	v_pk_add_f32 v[34:35], v[34:35], 0 op_sel_hi:[1,0]
	v_cvt_pk_bf16_f32 v76, v76, v77
	v_cvt_pk_bf16_f32 v77, v84, v85
	global_store_dwordx4 v[78:79], v[74:77], off sc0 sc1
	v_pk_add_f32 v[24:25], v[24:25], 0 op_sel_hi:[1,0]
	v_pk_add_f32 v[22:23], v[22:23], 0 op_sel_hi:[1,0]
	v_pk_add_f32 v[74:75], v[68:69], 0 op_sel_hi:[1,0]
	v_pk_add_f32 v[68:69], v[66:67], 0 op_sel_hi:[1,0]
	v_cvt_pk_bf16_f32 v66, v70, v71
	v_cvt_pk_bf16_f32 v67, v72, v73
	v_pk_add_f32 v[18:19], v[18:19], 0 op_sel_hi:[1,0]
	v_cvt_pk_bf16_f32 v68, v68, v69
	v_cvt_pk_bf16_f32 v69, v74, v75
	global_store_dwordx4 v[78:79], v[66:69], off offset:256 sc0 sc1
	s_mov_b64 s[2:3], -1
	v_pk_add_f32 v[8:9], v[8:9], 0 op_sel_hi:[1,0]
	v_pk_add_f32 v[68:69], v[60:61], 0 op_sel_hi:[1,0]
	v_pk_add_f32 v[60:61], v[58:59], 0 op_sel_hi:[1,0]
	v_cvt_pk_bf16_f32 v58, v62, v63
	v_add_co_u32_e32 v62, vcc, s48, v144
	v_cvt_pk_bf16_f32 v59, v64, v65
	v_cvt_pk_bf16_f32 v60, v60, v61
	v_cvt_pk_bf16_f32 v61, v68, v69
	v_lshl_add_u64 v[66:67], v[144:145], 0, s[8:9]
	s_nop 0
	v_addc_co_u32_e32 v63, vcc, 0, v145, vcc
	global_store_dwordx4 v[62:63], v[58:61], off sc0 sc1
	v_pk_add_f32 v[6:7], v[6:7], 0 op_sel_hi:[1,0]
	s_nop 0
	v_pk_add_f32 v[58:59], v[48:49], 0 op_sel_hi:[1,0]
	v_pk_add_f32 v[48:49], v[46:47], 0 op_sel_hi:[1,0]
	v_cvt_pk_bf16_f32 v46, v54, v55
	v_cvt_pk_bf16_f32 v47, v56, v57
	s_nop 0
	v_cvt_pk_bf16_f32 v48, v48, v49
	v_cvt_pk_bf16_f32 v49, v58, v59
	global_store_dwordx4 v[66:67], v[46:49], off offset:256 sc0 sc1
	s_nop 1
	v_pk_add_f32 v[48:49], v[52:53], 0 op_sel_hi:[1,0]
	v_pk_add_f32 v[52:53], v[44:45], 0 op_sel_hi:[1,0]
	v_pk_add_f32 v[44:45], v[42:43], 0 op_sel_hi:[1,0]
	v_cvt_pk_bf16_f32 v42, v50, v51
	v_cvt_pk_bf16_f32 v43, v48, v49
	v_add_co_u32_e32 v48, vcc, s49, v144
	v_cvt_pk_bf16_f32 v44, v44, v45
	v_cvt_pk_bf16_f32 v45, v52, v53
	v_lshl_add_u64 v[46:47], v[144:145], 0, s[10:11]
	s_nop 0
	v_addc_co_u32_e32 v49, vcc, 0, v145, vcc
	global_store_dwordx4 v[48:49], v[42:45], off sc0 sc1
	s_nop 1
	v_pk_add_f32 v[42:43], v[32:33], 0 op_sel_hi:[1,0]
	v_pk_add_f32 v[32:33], v[30:31], 0 op_sel_hi:[1,0]
	v_cvt_pk_bf16_f32 v30, v38, v39
	v_cvt_pk_bf16_f32 v31, v40, v41
	s_nop 0
	v_cvt_pk_bf16_f32 v32, v32, v33
	v_cvt_pk_bf16_f32 v33, v42, v43
	global_store_dwordx4 v[46:47], v[30:33], off offset:256 sc0 sc1
	s_nop 1
	v_pk_add_f32 v[32:33], v[36:37], 0 op_sel_hi:[1,0]
	v_pk_add_f32 v[36:37], v[28:29], 0 op_sel_hi:[1,0]
	v_pk_add_f32 v[28:29], v[26:27], 0 op_sel_hi:[1,0]
	v_cvt_pk_bf16_f32 v26, v34, v35
	v_cvt_pk_bf16_f32 v27, v32, v33
	v_add_co_u32_e32 v32, vcc, s50, v144
	v_cvt_pk_bf16_f32 v28, v28, v29
	v_cvt_pk_bf16_f32 v29, v36, v37
	v_lshl_add_u64 v[30:31], v[144:145], 0, s[12:13]
	s_nop 0
	v_addc_co_u32_e32 v33, vcc, 0, v145, vcc
	global_store_dwordx4 v[32:33], v[26:29], off sc0 sc1
	s_nop 1
	v_pk_add_f32 v[26:27], v[16:17], 0 op_sel_hi:[1,0]
	v_pk_add_f32 v[16:17], v[14:15], 0 op_sel_hi:[1,0]
	v_cvt_pk_bf16_f32 v14, v22, v23
	v_cvt_pk_bf16_f32 v15, v24, v25
	s_nop 0
	v_cvt_pk_bf16_f32 v16, v16, v17
	v_cvt_pk_bf16_f32 v17, v26, v27
	global_store_dwordx4 v[30:31], v[14:17], off offset:256 sc0 sc1
	s_nop 1
	v_pk_add_f32 v[16:17], v[20:21], 0 op_sel_hi:[1,0]
	v_pk_add_f32 v[20:21], v[12:13], 0 op_sel_hi:[1,0]
	v_pk_add_f32 v[12:13], v[10:11], 0 op_sel_hi:[1,0]
	v_cvt_pk_bf16_f32 v10, v18, v19
	v_cvt_pk_bf16_f32 v11, v16, v17
	v_add_co_u32_e32 v16, vcc, s51, v144
	v_lshl_add_u64 v[14:15], v[144:145], 0, s[14:15]
	s_nop 0
	v_addc_co_u32_e32 v17, vcc, 0, v145, vcc
	v_cvt_pk_bf16_f32 v12, v12, v13
	v_cvt_pk_bf16_f32 v13, v20, v21
	global_store_dwordx4 v[16:17], v[10:13], off sc0 sc1
	s_andn2_b64 vcc, exec, s[20:21]
	s_nop 0
	v_pk_add_f32 v[10:11], v[4:5], 0 op_sel_hi:[1,0]
	v_pk_add_f32 v[4:5], v[2:3], 0 op_sel_hi:[1,0]
	v_cvt_pk_bf16_f32 v2, v6, v7
	v_cvt_pk_bf16_f32 v3, v8, v9
	s_nop 0
	v_cvt_pk_bf16_f32 v4, v4, v5
	v_cvt_pk_bf16_f32 v5, v10, v11
	global_store_dwordx4 v[14:15], v[2:5], off offset:256 sc0 sc1
	s_cbranch_vccnz .LBB0_1435
	s_andn2_b64 vcc, exec, s[4:5]
	s_cbranch_vccnz .LBB0_1434
	s_barrier
	s_branch .LBB0_1434
